# pool mixer staging: 9 masked loads in flight then LDS writes (was load-wait-write per iteration)
# baseline (speedup 1.0000x reference)
.LBB0_587:
	s_mov_b64 s[4:5], exec
	v_mov_b32_e32 v20, 0
	v_mov_b32_e32 v21, 0
	v_mov_b32_e32 v22, 0
	v_mov_b32_e32 v23, 0
	v_mov_b32_e32 v24, 0
	v_mov_b32_e32 v25, 0
	v_mov_b32_e32 v26, 0
	v_mov_b32_e32 v27, 0
	v_mov_b32_e32 v28, 0
	v_mov_b32_e32 v29, 0
	v_mov_b32_e32 v30, 0
	v_mov_b32_e32 v31, 0
	v_mov_b32_e32 v32, 0
	v_mov_b32_e32 v33, 0
	v_mov_b32_e32 v34, 0
	v_mov_b32_e32 v35, 0
	v_mov_b32_e32 v36, 0
	v_mov_b32_e32 v37, 0
	v_mov_b32_e32 v38, 0
	v_mov_b32_e32 v39, 0
	v_mov_b32_e32 v40, 0
	v_mov_b32_e32 v41, 0
	v_mov_b32_e32 v42, 0
	v_mov_b32_e32 v43, 0
	v_mov_b32_e32 v44, 0
	v_mov_b32_e32 v45, 0
	v_mov_b32_e32 v46, 0
	v_mov_b32_e32 v47, 0
	v_mov_b32_e32 v48, 0
	v_mov_b32_e32 v49, 0
	v_mov_b32_e32 v50, 0
	v_mov_b32_e32 v51, 0
	v_mov_b32_e32 v52, 0
	v_mov_b32_e32 v53, 0
	v_mov_b32_e32 v54, 0
	v_mov_b32_e32 v55, 0
	v_add_u32_e32 v56, 0x0, v10
	v_add_u32_e32 v57, 0, v8
	s_mov_b64 s[6:7], s[4:5]
	v_cmp_le_i32_e32 vcc, s9, v57
	s_and_b64 exec, s[6:7], vcc
	v_mad_i64_i32 v[58:59], s[10:11], v57, s19, v[6:7]
	global_load_dwordx4 v[20:23], v[58:59], off
	s_mov_b64 exec, s[4:5]
	v_add_u32_e32 v56, 0x200, v10
	v_add_u32_e32 v57, 16, v8
	v_cmp_ge_u32_e32 vcc, s21, v56
	s_and_b64 s[6:7], vcc, s[4:5]
	v_cmp_le_i32_e32 vcc, s9, v57
	s_and_b64 exec, s[6:7], vcc
	v_mad_i64_i32 v[58:59], s[10:11], v57, s19, v[6:7]
	global_load_dwordx4 v[24:27], v[58:59], off
	s_mov_b64 exec, s[4:5]
	v_add_u32_e32 v56, 0x400, v10
	v_add_u32_e32 v57, 32, v8
	v_cmp_ge_u32_e32 vcc, s21, v56
	s_and_b64 s[6:7], vcc, s[4:5]
	v_cmp_le_i32_e32 vcc, s9, v57
	s_and_b64 exec, s[6:7], vcc
	v_mad_i64_i32 v[58:59], s[10:11], v57, s19, v[6:7]
	global_load_dwordx4 v[28:31], v[58:59], off
	s_mov_b64 exec, s[4:5]
	v_add_u32_e32 v56, 0x600, v10
	v_add_u32_e32 v57, 48, v8
	v_cmp_ge_u32_e32 vcc, s21, v56
	s_and_b64 s[6:7], vcc, s[4:5]
	v_cmp_le_i32_e32 vcc, s9, v57
	s_and_b64 exec, s[6:7], vcc
	v_mad_i64_i32 v[58:59], s[10:11], v57, s19, v[6:7]
	global_load_dwordx4 v[32:35], v[58:59], off
	s_mov_b64 exec, s[4:5]
	v_add_u32_e32 v56, 0x800, v10
	v_add_u32_e32 v57, 64, v8
	v_cmp_ge_u32_e32 vcc, s21, v56
	s_and_b64 s[6:7], vcc, s[4:5]
	v_cmp_le_i32_e32 vcc, s9, v57
	s_and_b64 exec, s[6:7], vcc
	v_mad_i64_i32 v[58:59], s[10:11], v57, s19, v[6:7]
	global_load_dwordx4 v[36:39], v[58:59], off
	s_mov_b64 exec, s[4:5]
	v_add_u32_e32 v56, 0xa00, v10
	v_add_u32_e32 v57, 80, v8
	v_cmp_ge_u32_e32 vcc, s21, v56
	s_and_b64 s[6:7], vcc, s[4:5]
	v_cmp_le_i32_e32 vcc, s9, v57
	s_and_b64 exec, s[6:7], vcc
	v_mad_i64_i32 v[58:59], s[10:11], v57, s19, v[6:7]
	global_load_dwordx4 v[40:43], v[58:59], off
	s_mov_b64 exec, s[4:5]
	v_add_u32_e32 v56, 0xc00, v10
	v_add_u32_e32 v57, 96, v8
	v_cmp_ge_u32_e32 vcc, s21, v56
	s_and_b64 s[6:7], vcc, s[4:5]
	v_cmp_le_i32_e32 vcc, s9, v57
	s_and_b64 exec, s[6:7], vcc
	v_mad_i64_i32 v[58:59], s[10:11], v57, s19, v[6:7]
	global_load_dwordx4 v[44:47], v[58:59], off
	s_mov_b64 exec, s[4:5]
	v_add_u32_e32 v56, 0xe00, v10
	v_add_u32_e32 v57, 112, v8
	v_cmp_ge_u32_e32 vcc, s21, v56
	s_and_b64 s[6:7], vcc, s[4:5]
	v_cmp_le_i32_e32 vcc, s9, v57
	s_and_b64 exec, s[6:7], vcc
	v_mad_i64_i32 v[58:59], s[10:11], v57, s19, v[6:7]
	global_load_dwordx4 v[48:51], v[58:59], off
	s_mov_b64 exec, s[4:5]
	v_add_u32_e32 v56, 0x1000, v10
	v_add_u32_e32 v57, 128, v8
	v_cmp_ge_u32_e32 vcc, s21, v56
	s_and_b64 s[6:7], vcc, s[4:5]
	v_cmp_le_i32_e32 vcc, s9, v57
	s_and_b64 exec, s[6:7], vcc
	v_mad_i64_i32 v[58:59], s[10:11], v57, s19, v[6:7]
	global_load_dwordx4 v[52:55], v[58:59], off
	s_mov_b64 exec, s[4:5]
	s_waitcnt vmcnt(0)
	ds_write_b128 v9, v[20:23]
	v_add_u32_e32 v56, 0x200, v10
	v_cmp_ge_u32_e32 vcc, s21, v56
	s_and_b64 exec, vcc, s[4:5]
	ds_write_b128 v9, v[24:27] offset:8192
	v_add_u32_e32 v56, 0x400, v10
	v_cmp_ge_u32_e32 vcc, s21, v56
	s_and_b64 exec, vcc, s[4:5]
	ds_write_b128 v9, v[28:31] offset:16384
	v_add_u32_e32 v56, 0x600, v10
	v_cmp_ge_u32_e32 vcc, s21, v56
	s_and_b64 exec, vcc, s[4:5]
	ds_write_b128 v9, v[32:35] offset:24576
	v_add_u32_e32 v56, 0x800, v10
	v_cmp_ge_u32_e32 vcc, s21, v56
	s_and_b64 exec, vcc, s[4:5]
	ds_write_b128 v9, v[36:39] offset:32768
	v_add_u32_e32 v56, 0xa00, v10
	v_cmp_ge_u32_e32 vcc, s21, v56
	s_and_b64 exec, vcc, s[4:5]
	ds_write_b128 v9, v[40:43] offset:40960
	v_add_u32_e32 v56, 0xc00, v10
	v_cmp_ge_u32_e32 vcc, s21, v56
	s_and_b64 exec, vcc, s[4:5]
	ds_write_b128 v9, v[44:47] offset:49152
	v_add_u32_e32 v56, 0xe00, v10
	v_cmp_ge_u32_e32 vcc, s21, v56
	s_and_b64 exec, vcc, s[4:5]
	ds_write_b128 v9, v[48:51] offset:57344
	v_add_u32_e32 v56, 0x1000, v10
	v_cmp_ge_u32_e32 vcc, s21, v56
	s_and_b64 exec, vcc, s[4:5]
	v_add_u32_e32 v57, 0x10000, v9
	ds_write_b128 v57, v[52:55]
	s_mov_b64 exec, s[4:5]
	s_branch .LBB0_589

.LBB0_1370:
	s_mov_b64 s[4:5], exec
	v_mov_b32_e32 v20, 0
	v_mov_b32_e32 v21, 0
	v_mov_b32_e32 v22, 0
	v_mov_b32_e32 v23, 0
	v_mov_b32_e32 v24, 0
	v_mov_b32_e32 v25, 0
	v_mov_b32_e32 v26, 0
	v_mov_b32_e32 v27, 0
	v_mov_b32_e32 v28, 0
	v_mov_b32_e32 v29, 0
	v_mov_b32_e32 v30, 0
	v_mov_b32_e32 v31, 0
	v_mov_b32_e32 v32, 0
	v_mov_b32_e32 v33, 0
	v_mov_b32_e32 v34, 0
	v_mov_b32_e32 v35, 0
	v_mov_b32_e32 v36, 0
	v_mov_b32_e32 v37, 0
	v_mov_b32_e32 v38, 0
	v_mov_b32_e32 v39, 0
	v_mov_b32_e32 v40, 0
	v_mov_b32_e32 v41, 0
	v_mov_b32_e32 v42, 0
	v_mov_b32_e32 v43, 0
	v_mov_b32_e32 v44, 0
	v_mov_b32_e32 v45, 0
	v_mov_b32_e32 v46, 0
	v_mov_b32_e32 v47, 0
	v_mov_b32_e32 v48, 0
	v_mov_b32_e32 v49, 0
	v_mov_b32_e32 v50, 0
	v_mov_b32_e32 v51, 0
	v_mov_b32_e32 v52, 0
	v_mov_b32_e32 v53, 0
	v_mov_b32_e32 v54, 0
	v_mov_b32_e32 v55, 0
	v_add_u32_e32 v56, 0x0, v10
	v_add_u32_e32 v57, 0, v8
	s_mov_b64 s[6:7], s[4:5]
	v_cmp_le_i32_e32 vcc, s11, v57
	s_and_b64 exec, s[6:7], vcc
	v_mad_i64_i32 v[58:59], s[12:13], v57, s21, v[6:7]
	global_load_dwordx4 v[20:23], v[58:59], off
	s_mov_b64 exec, s[4:5]
	v_add_u32_e32 v56, 0x200, v10
	v_add_u32_e32 v57, 16, v8
	v_cmp_ge_u32_e32 vcc, s23, v56
	s_and_b64 s[6:7], vcc, s[4:5]
	v_cmp_le_i32_e32 vcc, s11, v57
	s_and_b64 exec, s[6:7], vcc
	v_mad_i64_i32 v[58:59], s[12:13], v57, s21, v[6:7]
	global_load_dwordx4 v[24:27], v[58:59], off
	s_mov_b64 exec, s[4:5]
	v_add_u32_e32 v56, 0x400, v10
	v_add_u32_e32 v57, 32, v8
	v_cmp_ge_u32_e32 vcc, s23, v56
	s_and_b64 s[6:7], vcc, s[4:5]
	v_cmp_le_i32_e32 vcc, s11, v57
	s_and_b64 exec, s[6:7], vcc
	v_mad_i64_i32 v[58:59], s[12:13], v57, s21, v[6:7]
	global_load_dwordx4 v[28:31], v[58:59], off
	s_mov_b64 exec, s[4:5]
	v_add_u32_e32 v56, 0x600, v10
	v_add_u32_e32 v57, 48, v8
	v_cmp_ge_u32_e32 vcc, s23, v56
	s_and_b64 s[6:7], vcc, s[4:5]
	v_cmp_le_i32_e32 vcc, s11, v57
	s_and_b64 exec, s[6:7], vcc
	v_mad_i64_i32 v[58:59], s[12:13], v57, s21, v[6:7]
	global_load_dwordx4 v[32:35], v[58:59], off
	s_mov_b64 exec, s[4:5]
	v_add_u32_e32 v56, 0x800, v10
	v_add_u32_e32 v57, 64, v8
	v_cmp_ge_u32_e32 vcc, s23, v56
	s_and_b64 s[6:7], vcc, s[4:5]
	v_cmp_le_i32_e32 vcc, s11, v57
	s_and_b64 exec, s[6:7], vcc
	v_mad_i64_i32 v[58:59], s[12:13], v57, s21, v[6:7]
	global_load_dwordx4 v[36:39], v[58:59], off
	s_mov_b64 exec, s[4:5]
	v_add_u32_e32 v56, 0xa00, v10
	v_add_u32_e32 v57, 80, v8
	v_cmp_ge_u32_e32 vcc, s23, v56
	s_and_b64 s[6:7], vcc, s[4:5]
	v_cmp_le_i32_e32 vcc, s11, v57
	s_and_b64 exec, s[6:7], vcc
	v_mad_i64_i32 v[58:59], s[12:13], v57, s21, v[6:7]
	global_load_dwordx4 v[40:43], v[58:59], off
	s_mov_b64 exec, s[4:5]
	v_add_u32_e32 v56, 0xc00, v10
	v_add_u32_e32 v57, 96, v8
	v_cmp_ge_u32_e32 vcc, s23, v56
	s_and_b64 s[6:7], vcc, s[4:5]
	v_cmp_le_i32_e32 vcc, s11, v57
	s_and_b64 exec, s[6:7], vcc
	v_mad_i64_i32 v[58:59], s[12:13], v57, s21, v[6:7]
	global_load_dwordx4 v[44:47], v[58:59], off
	s_mov_b64 exec, s[4:5]
	v_add_u32_e32 v56, 0xe00, v10
	v_add_u32_e32 v57, 112, v8
	v_cmp_ge_u32_e32 vcc, s23, v56
	s_and_b64 s[6:7], vcc, s[4:5]
	v_cmp_le_i32_e32 vcc, s11, v57
	s_and_b64 exec, s[6:7], vcc
	v_mad_i64_i32 v[58:59], s[12:13], v57, s21, v[6:7]
	global_load_dwordx4 v[48:51], v[58:59], off
	s_mov_b64 exec, s[4:5]
	v_add_u32_e32 v56, 0x1000, v10
	v_add_u32_e32 v57, 128, v8
	v_cmp_ge_u32_e32 vcc, s23, v56
	s_and_b64 s[6:7], vcc, s[4:5]
	v_cmp_le_i32_e32 vcc, s11, v57
	s_and_b64 exec, s[6:7], vcc
	v_mad_i64_i32 v[58:59], s[12:13], v57, s21, v[6:7]
	global_load_dwordx4 v[52:55], v[58:59], off
	s_mov_b64 exec, s[4:5]
	s_waitcnt vmcnt(0)
	ds_write_b128 v9, v[20:23]
	v_add_u32_e32 v56, 0x200, v10
	v_cmp_ge_u32_e32 vcc, s23, v56
	s_and_b64 exec, vcc, s[4:5]
	ds_write_b128 v9, v[24:27] offset:8192
	v_add_u32_e32 v56, 0x400, v10
	v_cmp_ge_u32_e32 vcc, s23, v56
	s_and_b64 exec, vcc, s[4:5]
	ds_write_b128 v9, v[28:31] offset:16384
	v_add_u32_e32 v56, 0x600, v10
	v_cmp_ge_u32_e32 vcc, s23, v56
	s_and_b64 exec, vcc, s[4:5]
	ds_write_b128 v9, v[32:35] offset:24576
	v_add_u32_e32 v56, 0x800, v10
	v_cmp_ge_u32_e32 vcc, s23, v56
	s_and_b64 exec, vcc, s[4:5]
	ds_write_b128 v9, v[36:39] offset:32768
	v_add_u32_e32 v56, 0xa00, v10
	v_cmp_ge_u32_e32 vcc, s23, v56
	s_and_b64 exec, vcc, s[4:5]
	ds_write_b128 v9, v[40:43] offset:40960
	v_add_u32_e32 v56, 0xc00, v10
	v_cmp_ge_u32_e32 vcc, s23, v56
	s_and_b64 exec, vcc, s[4:5]
	ds_write_b128 v9, v[44:47] offset:49152
	v_add_u32_e32 v56, 0xe00, v10
	v_cmp_ge_u32_e32 vcc, s23, v56
	s_and_b64 exec, vcc, s[4:5]
	ds_write_b128 v9, v[48:51] offset:57344
	v_add_u32_e32 v56, 0x1000, v10
	v_cmp_ge_u32_e32 vcc, s23, v56
	s_and_b64 exec, vcc, s[4:5]
	v_add_u32_e32 v57, 0x10000, v9
	ds_write_b128 v57, v[52:55]
	s_mov_b64 exec, s[4:5]
	s_branch .LBB0_1372
